# k15: k14 + accumulator zeroing with v_mov_b64 (5 GEMM instances)
# speedup vs baseline: 1.0088x; 1.0049x over previous
; template <class Epi>
; __device__ __forceinline__ void gemm_phase(LAS unsigned char* lds, const Gemm g, const Epi& E) {
;     ...
;         const bool has_next = S.next(ui + 1, nxt);
;         const char* nA = has_next ? (const char*)g.A + (size_t)g.mapA.src(nxt.pm) * tstepA + (size_t)nxt.pn * g.a_pn_step : cA;
;         const char* nB = has_next ? (const char*)g.Bt + (size_t)g.mapB.src(nxt.pn) * tstepB : cB;
;     ...
; #pragma unroll
;         for (int a = 0; a < 2; ++a)
; #pragma unroll
;             for (int b = 0; b < 2; ++b)
; #pragma unroll
;                 for (int m = 0; m < 4; ++m)
; #pragma unroll
;                     for (int n = 0; n < 2; ++n) acc[a][b][m][n] = (f32x4){0.f, 0.f, 0.f, 0.f};
.LBB0_295:
	s_lshl_b64 s[0:1], s[8:9], 17
	v_mov_b64_e32 v[2:3], s[76:77]
	s_add_u32 s5, s91, s0
	v_cmp_lt_i64_e32 vcc, s[12:13], v[2:3]
	s_addc_u32 s9, s25, s1
	s_and_b64 s[0:1], vcc, exec
	v_mov_b32_e32 v2, 0
	s_cselect_b32 s13, s9, s15
	s_cselect_b32 s12, s5, s14
	s_mov_b32 s5, 0
	s_mov_b64 s[28:29], -1
	s_mov_b64 s[58:59], 0
	v_mov_b32_e32 v3, v2
	v_mov_b64_e32 v[4:5], v[2:3]
	v_mov_b64_e32 v[6:7], v[2:3]
	v_mov_b64_e32 v[8:9], v[2:3]
	v_mov_b64_e32 v[10:11], v[2:3]
	v_mov_b64_e32 v[12:13], v[2:3]
	v_mov_b64_e32 v[14:15], v[2:3]
	v_mov_b64_e32 v[16:17], v[2:3]
	v_mov_b64_e32 v[18:19], v[2:3]
	v_mov_b64_e32 v[20:21], v[2:3]
	v_mov_b64_e32 v[22:23], v[2:3]
	v_mov_b64_e32 v[24:25], v[2:3]
	v_mov_b64_e32 v[26:27], v[2:3]
	v_mov_b64_e32 v[28:29], v[2:3]
	v_mov_b64_e32 v[30:31], v[2:3]
	v_mov_b64_e32 v[32:33], v[2:3]
	v_mov_b64_e32 v[34:35], v[2:3]
	v_mov_b64_e32 v[36:37], v[2:3]
	v_mov_b64_e32 v[38:39], v[2:3]
	v_mov_b64_e32 v[40:41], v[2:3]
	v_mov_b64_e32 v[42:43], v[2:3]
	v_mov_b64_e32 v[44:45], v[2:3]
	v_mov_b64_e32 v[46:47], v[2:3]
	v_mov_b64_e32 v[48:49], v[2:3]
	v_mov_b64_e32 v[50:51], v[2:3]
	v_mov_b64_e32 v[52:53], v[2:3]
	v_mov_b64_e32 v[54:55], v[2:3]
	v_mov_b64_e32 v[56:57], v[2:3]
	v_mov_b64_e32 v[58:59], v[2:3]
	v_mov_b64_e32 v[60:61], v[2:3]
	v_mov_b64_e32 v[62:63], v[2:3]
	v_mov_b64_e32 v[64:65], v[2:3]
	v_mov_b64_e32 v[66:67], v[2:3]
	v_mov_b64_e32 v[68:69], v[2:3]
	v_mov_b64_e32 v[70:71], v[2:3]
	v_mov_b64_e32 v[72:73], v[2:3]
	v_mov_b64_e32 v[74:75], v[2:3]
	v_mov_b64_e32 v[76:77], v[2:3]
	v_mov_b64_e32 v[78:79], v[2:3]
	v_mov_b64_e32 v[80:81], v[2:3]
	v_mov_b64_e32 v[82:83], v[2:3]
	v_mov_b64_e32 v[84:85], v[2:3]
	v_mov_b64_e32 v[86:87], v[2:3]
	v_mov_b64_e32 v[88:89], v[2:3]
	v_mov_b64_e32 v[90:91], v[2:3]
	v_mov_b64_e32 v[92:93], v[2:3]
	v_mov_b64_e32 v[94:95], v[2:3]
	v_mov_b64_e32 v[96:97], v[2:3]
	v_mov_b64_e32 v[98:99], v[2:3]
	v_mov_b64_e32 v[100:101], v[2:3]
	v_mov_b64_e32 v[102:103], v[2:3]
	v_mov_b64_e32 v[104:105], v[2:3]
	v_mov_b64_e32 v[106:107], v[2:3]
	v_mov_b64_e32 v[108:109], v[2:3]
	v_mov_b64_e32 v[110:111], v[2:3]
	v_mov_b64_e32 v[112:113], v[2:3]
	v_mov_b64_e32 v[114:115], v[2:3]
	v_mov_b64_e32 v[116:117], v[2:3]
	v_mov_b64_e32 v[118:119], v[2:3]
	v_mov_b64_e32 v[120:121], v[2:3]
	v_mov_b64_e32 v[122:123], v[2:3]
	v_mov_b64_e32 v[124:125], v[2:3]
	v_mov_b64_e32 v[126:127], v[2:3]
	v_mov_b64_e32 v[128:129], v[2:3]

; template <class Epi>
; __device__ __forceinline__ void gemm_phase(LAS unsigned char* lds, const Gemm g, const Epi& E) {
;     ...
;         const bool has_next = S.next(ui + 1, nxt);
;         const char* nA = has_next ? (const char*)g.A + (size_t)g.mapA.src(nxt.pm) * tstepA + (size_t)nxt.pn * g.a_pn_step : cA;
;         const char* nB = has_next ? (const char*)g.Bt + (size_t)g.mapB.src(nxt.pn) * tstepB : cB;
;     ...
; #pragma unroll
;         for (int a = 0; a < 2; ++a)
; #pragma unroll
;             for (int b = 0; b < 2; ++b)
; #pragma unroll
;                 for (int m = 0; m < 4; ++m)
; #pragma unroll
;                     for (int n = 0; n < 2; ++n) acc[a][b][m][n] = (f32x4){0.f, 0.f, 0.f, 0.f};
.LBB0_330:
	s_ashr_i32 s15, s14, 31
	s_lshl_b64 s[52:53], s[14:15], 19
	s_add_u32 s15, s92, s52
	s_addc_u32 s52, s93, s53
	s_and_b64 s[4:5], s[4:5], exec
	s_cselect_b32 s59, s52, s65
	s_cselect_b32 s58, s15, s64
	s_add_u32 s4, s60, 0x40080
	s_addc_u32 s5, s61, 0
	s_add_u32 s15, s64, 0x100
	v_mov_b32_e32 v2, 0
	s_addc_u32 s52, s65, 0
	s_mov_b32 s53, -2
	v_mov_b32_e32 v3, v2
	v_mov_b64_e32 v[4:5], v[2:3]
	v_mov_b64_e32 v[6:7], v[2:3]
	v_mov_b64_e32 v[8:9], v[2:3]
	v_mov_b64_e32 v[10:11], v[2:3]
	v_mov_b64_e32 v[12:13], v[2:3]
	v_mov_b64_e32 v[14:15], v[2:3]
	v_mov_b64_e32 v[16:17], v[2:3]
	v_mov_b64_e32 v[18:19], v[2:3]
	v_mov_b64_e32 v[20:21], v[2:3]
	v_mov_b64_e32 v[22:23], v[2:3]
	v_mov_b64_e32 v[24:25], v[2:3]
	v_mov_b64_e32 v[26:27], v[2:3]
	v_mov_b64_e32 v[28:29], v[2:3]
	v_mov_b64_e32 v[30:31], v[2:3]
	v_mov_b64_e32 v[32:33], v[2:3]
	v_mov_b64_e32 v[34:35], v[2:3]
	v_mov_b64_e32 v[36:37], v[2:3]
	v_mov_b64_e32 v[38:39], v[2:3]
	v_mov_b64_e32 v[40:41], v[2:3]
	v_mov_b64_e32 v[42:43], v[2:3]
	v_mov_b64_e32 v[44:45], v[2:3]
	v_mov_b64_e32 v[46:47], v[2:3]
	v_mov_b64_e32 v[48:49], v[2:3]
	v_mov_b64_e32 v[50:51], v[2:3]
	v_mov_b64_e32 v[52:53], v[2:3]
	v_mov_b64_e32 v[54:55], v[2:3]
	v_mov_b64_e32 v[56:57], v[2:3]
	v_mov_b64_e32 v[58:59], v[2:3]
	v_mov_b64_e32 v[60:61], v[2:3]
	v_mov_b64_e32 v[62:63], v[2:3]
	v_mov_b64_e32 v[64:65], v[2:3]
	v_mov_b64_e32 v[66:67], v[2:3]
	v_mov_b64_e32 v[68:69], v[2:3]
	v_mov_b64_e32 v[70:71], v[2:3]
	v_mov_b64_e32 v[72:73], v[2:3]
	v_mov_b64_e32 v[78:79], v[2:3]
	v_mov_b64_e32 v[80:81], v[2:3]
	v_mov_b64_e32 v[90:91], v[2:3]
	v_mov_b64_e32 v[92:93], v[2:3]
	v_mov_b64_e32 v[98:99], v[2:3]
	v_mov_b64_e32 v[100:101], v[2:3]
	v_mov_b64_e32 v[102:103], v[2:3]
	v_mov_b64_e32 v[104:105], v[2:3]
	v_mov_b64_e32 v[114:115], v[2:3]
	v_mov_b64_e32 v[116:117], v[2:3]
	v_mov_b64_e32 v[118:119], v[2:3]
	v_mov_b64_e32 v[120:121], v[2:3]
	v_mov_b64_e32 v[122:123], v[2:3]
	v_mov_b64_e32 v[124:125], v[2:3]
	v_mov_b64_e32 v[126:127], v[2:3]
	v_mov_b64_e32 v[128:129], v[2:3]
	v_mov_b64_e32 v[138:139], v[2:3]
	v_mov_b64_e32 v[140:141], v[2:3]
	v_mov_b64_e32 v[142:143], v[2:3]
	v_mov_b64_e32 v[144:145], v[2:3]
	v_mov_b64_e32 v[146:147], v[2:3]
	v_mov_b64_e32 v[148:149], v[2:3]
	v_mov_b64_e32 v[150:151], v[2:3]
	v_mov_b64_e32 v[152:153], v[2:3]
	v_mov_b64_e32 v[162:163], v[2:3]
	v_mov_b64_e32 v[164:165], v[2:3]
	v_mov_b64_e32 v[166:167], v[2:3]
	v_mov_b64_e32 v[168:169], v[2:3]

; template <class Epi>
; __device__ __forceinline__ void gemm_phase(LAS unsigned char* lds, const Gemm g, const Epi& E) {
;     ...
;         const bool has_next = S.next(ui + 1, nxt);
;         const char* nA = has_next ? (const char*)g.A + (size_t)g.mapA.src(nxt.pm) * tstepA + (size_t)nxt.pn * g.a_pn_step : cA;
;         const char* nB = has_next ? (const char*)g.Bt + (size_t)g.mapB.src(nxt.pn) * tstepB : cB;
;     ...
; #pragma unroll
;         for (int a = 0; a < 2; ++a)
; #pragma unroll
;             for (int b = 0; b < 2; ++b)
; #pragma unroll
;                 for (int m = 0; m < 4; ++m)
; #pragma unroll
;                     for (int n = 0; n < 2; ++n) acc[a][b][m][n] = (f32x4){0.f, 0.f, 0.f, 0.f};
.LBB0_494:
	s_ashr_i32 s7, s6, 31
	s_lshl_b64 s[16:17], s[6:7], 20
	s_add_u32 s7, s18, s16
	s_addc_u32 s16, s24, s17
	s_and_b64 s[4:5], s[4:5], exec
	s_cselect_b32 s5, s16, s15
	s_cselect_b32 s4, s7, s14
	s_add_u32 s12, s12, 0x80080
	s_addc_u32 s13, s13, 0
	s_add_u32 s7, s14, 0x100
	v_mov_b32_e32 v2, 0
	s_addc_u32 s64, s15, 0
	s_mov_b32 s65, -2
	v_mov_b32_e32 v3, v2
	v_mov_b64_e32 v[4:5], v[2:3]
	v_mov_b64_e32 v[6:7], v[2:3]
	v_mov_b64_e32 v[8:9], v[2:3]
	v_mov_b64_e32 v[10:11], v[2:3]
	v_mov_b64_e32 v[12:13], v[2:3]
	v_mov_b64_e32 v[14:15], v[2:3]
	v_mov_b64_e32 v[16:17], v[2:3]
	v_mov_b64_e32 v[18:19], v[2:3]
	v_mov_b64_e32 v[20:21], v[2:3]
	v_mov_b64_e32 v[22:23], v[2:3]
	v_mov_b64_e32 v[24:25], v[2:3]
	v_mov_b64_e32 v[26:27], v[2:3]
	v_mov_b64_e32 v[28:29], v[2:3]
	v_mov_b64_e32 v[30:31], v[2:3]
	v_mov_b64_e32 v[32:33], v[2:3]
	v_mov_b64_e32 v[34:35], v[2:3]
	v_mov_b64_e32 v[36:37], v[2:3]
	v_mov_b64_e32 v[38:39], v[2:3]
	v_mov_b64_e32 v[40:41], v[2:3]
	v_mov_b64_e32 v[42:43], v[2:3]
	v_mov_b64_e32 v[44:45], v[2:3]
	v_mov_b64_e32 v[46:47], v[2:3]
	v_mov_b64_e32 v[48:49], v[2:3]
	v_mov_b64_e32 v[50:51], v[2:3]
	v_mov_b64_e32 v[52:53], v[2:3]
	v_mov_b64_e32 v[54:55], v[2:3]
	v_mov_b64_e32 v[56:57], v[2:3]
	v_mov_b64_e32 v[58:59], v[2:3]
	v_mov_b64_e32 v[60:61], v[2:3]
	v_mov_b64_e32 v[62:63], v[2:3]
	v_mov_b64_e32 v[64:65], v[2:3]
	v_mov_b64_e32 v[66:67], v[2:3]
	v_mov_b64_e32 v[68:69], v[2:3]
	v_mov_b64_e32 v[70:71], v[2:3]
	v_mov_b64_e32 v[72:73], v[2:3]
	v_mov_b64_e32 v[74:75], v[2:3]
	v_mov_b64_e32 v[76:77], v[2:3]
	v_mov_b64_e32 v[78:79], v[2:3]
	v_mov_b64_e32 v[80:81], v[2:3]
	v_mov_b64_e32 v[82:83], v[2:3]
	v_mov_b64_e32 v[84:85], v[2:3]
	v_mov_b64_e32 v[86:87], v[2:3]
	v_mov_b64_e32 v[88:89], v[2:3]
	v_mov_b64_e32 v[90:91], v[2:3]
	v_mov_b64_e32 v[92:93], v[2:3]
	v_mov_b64_e32 v[94:95], v[2:3]
	v_mov_b64_e32 v[96:97], v[2:3]
	v_mov_b64_e32 v[98:99], v[2:3]
	v_mov_b64_e32 v[100:101], v[2:3]
	v_mov_b64_e32 v[102:103], v[2:3]
	v_mov_b64_e32 v[104:105], v[2:3]
	v_mov_b64_e32 v[106:107], v[2:3]
	v_mov_b64_e32 v[108:109], v[2:3]
	v_mov_b64_e32 v[110:111], v[2:3]
	v_mov_b64_e32 v[112:113], v[2:3]
	v_mov_b64_e32 v[114:115], v[2:3]
	v_mov_b64_e32 v[116:117], v[2:3]
	v_mov_b64_e32 v[118:119], v[2:3]
	v_mov_b64_e32 v[120:121], v[2:3]
	v_mov_b64_e32 v[122:123], v[2:3]
	v_mov_b64_e32 v[124:125], v[2:3]
	v_mov_b64_e32 v[126:127], v[2:3]
	v_mov_b64_e32 v[128:129], v[2:3]

; template <class Epi>
; __device__ __forceinline__ void gemm_phase(LAS unsigned char* lds, const Gemm g, const Epi& E) {
;     ...
;         const bool has_next = S.next(ui + 1, nxt);
;         const char* nA = has_next ? (const char*)g.A + (size_t)g.mapA.src(nxt.pm) * tstepA + (size_t)nxt.pn * g.a_pn_step : cA;
;         const char* nB = has_next ? (const char*)g.Bt + (size_t)g.mapB.src(nxt.pn) * tstepB : cB;
;     ...
; #pragma unroll
;         for (int a = 0; a < 2; ++a)
; #pragma unroll
;             for (int b = 0; b < 2; ++b)
; #pragma unroll
;                 for (int m = 0; m < 4; ++m)
; #pragma unroll
;                     for (int n = 0; n < 2; ++n) acc[a][b][m][n] = (f32x4){0.f, 0.f, 0.f, 0.f};
.LBB0_524:
	s_ashr_i32 s7, s6, 31
	s_lshl_b64 s[16:17], s[6:7], 19
	s_add_u32 s7, s18, s16
	s_addc_u32 s16, s24, s17
	s_and_b64 s[4:5], s[4:5], exec
	s_cselect_b32 s5, s16, s15
	s_cselect_b32 s4, s7, s14
	s_add_u32 s12, s12, 0x40080
	s_addc_u32 s13, s13, 0
	s_add_u32 s7, s14, 0x100
	v_mov_b32_e32 v2, 0
	s_addc_u32 s65, s15, 0
	s_mov_b32 s66, -2
	v_mov_b32_e32 v3, v2
	v_mov_b64_e32 v[4:5], v[2:3]
	v_mov_b64_e32 v[6:7], v[2:3]
	v_mov_b64_e32 v[8:9], v[2:3]
	v_mov_b64_e32 v[10:11], v[2:3]
	v_mov_b64_e32 v[12:13], v[2:3]
	v_mov_b64_e32 v[14:15], v[2:3]
	v_mov_b64_e32 v[16:17], v[2:3]
	v_mov_b64_e32 v[18:19], v[2:3]
	v_mov_b64_e32 v[20:21], v[2:3]
	v_mov_b64_e32 v[22:23], v[2:3]
	v_mov_b64_e32 v[24:25], v[2:3]
	v_mov_b64_e32 v[26:27], v[2:3]
	v_mov_b64_e32 v[28:29], v[2:3]
	v_mov_b64_e32 v[30:31], v[2:3]
	v_mov_b64_e32 v[32:33], v[2:3]
	v_mov_b64_e32 v[34:35], v[2:3]
	v_mov_b64_e32 v[36:37], v[2:3]
	v_mov_b64_e32 v[38:39], v[2:3]
	v_mov_b64_e32 v[40:41], v[2:3]
	v_mov_b64_e32 v[42:43], v[2:3]
	v_mov_b64_e32 v[44:45], v[2:3]
	v_mov_b64_e32 v[46:47], v[2:3]
	v_mov_b64_e32 v[48:49], v[2:3]
	v_mov_b64_e32 v[50:51], v[2:3]
	v_mov_b64_e32 v[52:53], v[2:3]
	v_mov_b64_e32 v[54:55], v[2:3]
	v_mov_b64_e32 v[56:57], v[2:3]
	v_mov_b64_e32 v[58:59], v[2:3]
	v_mov_b64_e32 v[60:61], v[2:3]
	v_mov_b64_e32 v[62:63], v[2:3]
	v_mov_b64_e32 v[64:65], v[2:3]
	v_mov_b64_e32 v[66:67], v[2:3]
	v_mov_b64_e32 v[68:69], v[2:3]
	v_mov_b64_e32 v[70:71], v[2:3]
	v_mov_b64_e32 v[72:73], v[2:3]
	v_mov_b64_e32 v[74:75], v[2:3]
	v_mov_b64_e32 v[76:77], v[2:3]
	v_mov_b64_e32 v[78:79], v[2:3]
	v_mov_b64_e32 v[80:81], v[2:3]
	v_mov_b64_e32 v[82:83], v[2:3]
	v_mov_b64_e32 v[84:85], v[2:3]
	v_mov_b64_e32 v[86:87], v[2:3]
	v_mov_b64_e32 v[88:89], v[2:3]
	v_mov_b64_e32 v[90:91], v[2:3]
	v_mov_b64_e32 v[92:93], v[2:3]
	v_mov_b64_e32 v[94:95], v[2:3]
	v_mov_b64_e32 v[96:97], v[2:3]
	v_mov_b64_e32 v[98:99], v[2:3]
	v_mov_b64_e32 v[100:101], v[2:3]
	v_mov_b64_e32 v[102:103], v[2:3]
	v_mov_b64_e32 v[104:105], v[2:3]
	v_mov_b64_e32 v[106:107], v[2:3]
	v_mov_b64_e32 v[108:109], v[2:3]
	v_mov_b64_e32 v[110:111], v[2:3]
	v_mov_b64_e32 v[112:113], v[2:3]
	v_mov_b64_e32 v[114:115], v[2:3]
	v_mov_b64_e32 v[116:117], v[2:3]
	v_mov_b64_e32 v[118:119], v[2:3]
	v_mov_b64_e32 v[120:121], v[2:3]
	v_mov_b64_e32 v[122:123], v[2:3]
	v_mov_b64_e32 v[124:125], v[2:3]
	v_mov_b64_e32 v[126:127], v[2:3]
	v_mov_b64_e32 v[128:129], v[2:3]

; template <class Epi>
; __device__ __forceinline__ void gemm_phase(LAS unsigned char* lds, const Gemm g, const Epi& E) {
;     ...
; #pragma unroll
;         for (int a = 0; a < 2; ++a)
; #pragma unroll
;             for (int b = 0; b < 2; ++b)
; #pragma unroll
;                 for (int m = 0; m < 4; ++m)
; #pragma unroll
;                     for (int n = 0; n < 2; ++n) acc[a][b][m][n] = (f32x4){0.f, 0.f, 0.f, 0.f};
.LBB0_546:
	s_add_u32 s65, s10, 0x100
	v_mov_b32_e32 v2, 0
	s_addc_u32 s66, s11, 0
	s_mov_b32 s67, -2
	v_mov_b32_e32 v3, v2
	v_mov_b64_e32 v[4:5], v[2:3]
	v_mov_b64_e32 v[6:7], v[2:3]
	v_mov_b64_e32 v[8:9], v[2:3]
	v_mov_b64_e32 v[10:11], v[2:3]
	v_mov_b64_e32 v[12:13], v[2:3]
	v_mov_b64_e32 v[14:15], v[2:3]
	v_mov_b64_e32 v[16:17], v[2:3]
	v_mov_b64_e32 v[18:19], v[2:3]
	v_mov_b64_e32 v[20:21], v[2:3]
	v_mov_b64_e32 v[22:23], v[2:3]
	v_mov_b64_e32 v[24:25], v[2:3]
	v_mov_b64_e32 v[26:27], v[2:3]
	v_mov_b64_e32 v[28:29], v[2:3]
	v_mov_b64_e32 v[30:31], v[2:3]
	v_mov_b64_e32 v[32:33], v[2:3]
	v_mov_b64_e32 v[34:35], v[2:3]
	v_mov_b64_e32 v[36:37], v[2:3]
	v_mov_b64_e32 v[38:39], v[2:3]
	v_mov_b64_e32 v[40:41], v[2:3]
	v_mov_b64_e32 v[42:43], v[2:3]
	v_mov_b64_e32 v[44:45], v[2:3]
	v_mov_b64_e32 v[46:47], v[2:3]
	v_mov_b64_e32 v[48:49], v[2:3]
	v_mov_b64_e32 v[50:51], v[2:3]
	v_mov_b64_e32 v[52:53], v[2:3]
	v_mov_b64_e32 v[54:55], v[2:3]
	v_mov_b64_e32 v[56:57], v[2:3]
	v_mov_b64_e32 v[58:59], v[2:3]
	v_mov_b64_e32 v[60:61], v[2:3]
	v_mov_b64_e32 v[62:63], v[2:3]
	v_mov_b64_e32 v[64:65], v[2:3]
	v_mov_b64_e32 v[66:67], v[2:3]
	v_mov_b64_e32 v[68:69], v[2:3]
	v_mov_b64_e32 v[70:71], v[2:3]
	v_mov_b64_e32 v[72:73], v[2:3]
	v_mov_b64_e32 v[74:75], v[2:3]
	v_mov_b64_e32 v[76:77], v[2:3]
	v_mov_b64_e32 v[78:79], v[2:3]
	v_mov_b64_e32 v[80:81], v[2:3]
	v_mov_b64_e32 v[82:83], v[2:3]
	v_mov_b64_e32 v[84:85], v[2:3]
	v_mov_b64_e32 v[86:87], v[2:3]
	v_mov_b64_e32 v[88:89], v[2:3]
	v_mov_b64_e32 v[90:91], v[2:3]
	v_mov_b64_e32 v[92:93], v[2:3]
	v_mov_b64_e32 v[94:95], v[2:3]
	v_mov_b64_e32 v[96:97], v[2:3]
	v_mov_b64_e32 v[98:99], v[2:3]
	v_mov_b64_e32 v[100:101], v[2:3]
	v_mov_b64_e32 v[102:103], v[2:3]
	v_mov_b64_e32 v[104:105], v[2:3]
	v_mov_b64_e32 v[106:107], v[2:3]
	v_mov_b64_e32 v[108:109], v[2:3]
	v_mov_b64_e32 v[110:111], v[2:3]
	v_mov_b64_e32 v[112:113], v[2:3]
	v_mov_b64_e32 v[114:115], v[2:3]
	v_mov_b64_e32 v[116:117], v[2:3]
	v_mov_b64_e32 v[118:119], v[2:3]
	v_mov_b64_e32 v[120:121], v[2:3]
	v_mov_b64_e32 v[122:123], v[2:3]
	v_mov_b64_e32 v[124:125], v[2:3]
	v_mov_b64_e32 v[126:127], v[2:3]
	v_mov_b64_e32 v[128:129], v[2:3]
